# a0fast_v3 plus accumulator zeroing with v_mov_b64 (619 pairs) instead of v_mov_b32 pairs
# speedup vs baseline: 1.0102x; 1.0013x over previous
; template <class Epi, class Sched, bool ALIGN_EPI = false, bool SP2 = false>
; __device__ __forceinline__ void gemm_phase(PG8_LAS unsigned char* lds, const Gemm g, const Sched& S, const Epi& E, int wave_s_) {
;     ...
;     f32x4 acc[2][2][4][2];
; #pragma unroll
;     for (int a = 0; a < 2; ++a)
; #pragma unroll
;         for (int b = 0; b < 2; ++b)
; #pragma unroll
;             for (int m = 0; m < 4; ++m)
; #pragma unroll
;                 for (int n = 0; n < 2; ++n) acc[a][b][m][n] = (f32x4){0.f, 0.f, 0.f, 0.f};
;     ...
; #pragma unroll
;         for (int a = 0; a < 2; ++a)
; #pragma unroll
;             for (int b = 0; b < 2; ++b)
; #pragma unroll
;                 for (int m = 0; m < 4; ++m)
; #pragma unroll
;                     for (int n = 0; n < 2; ++n) acc[a][b][m][n] = (f32x4){0.f, 0.f, 0.f, 0.f};
.LBB0_206:
	s_add_u32 s17, s22, 0x100
	s_addc_u32 s48, s23, 0
	s_add_u32 s22, s24, 0x40080
	v_mov_b32_e32 v0, 0
	s_addc_u32 s23, s25, 0
	s_mov_b32 s49, -2
	v_mov_b32_e32 v1, v0
	v_mov_b64_e32 v[2:3], 0
	v_mov_b64_e32 v[8:9], 0
	v_mov_b64_e32 v[10:11], 0
	v_mov_b64_e32 v[16:17], 0
	v_mov_b64_e32 v[18:19], 0
	v_mov_b64_e32 v[24:25], 0
	v_mov_b64_e32 v[26:27], 0
	v_mov_b64_e32 v[32:33], 0
	v_mov_b64_e32 v[34:35], 0
	v_mov_b64_e32 v[40:41], 0
	v_mov_b64_e32 v[42:43], 0
	v_mov_b64_e32 v[48:49], 0
	v_mov_b64_e32 v[50:51], 0
	v_mov_b64_e32 v[56:57], 0
	v_mov_b64_e32 v[58:59], 0
	v_mov_b64_e32 v[4:5], 0
	v_mov_b64_e32 v[6:7], 0
	v_mov_b64_e32 v[12:13], 0
	v_mov_b64_e32 v[14:15], 0
	v_mov_b64_e32 v[20:21], 0
	v_mov_b64_e32 v[22:23], 0
	v_mov_b64_e32 v[28:29], 0
	v_mov_b64_e32 v[30:31], 0
	v_mov_b64_e32 v[36:37], 0
	v_mov_b64_e32 v[38:39], 0
	v_mov_b64_e32 v[44:45], 0
	v_mov_b64_e32 v[46:47], 0
	v_mov_b64_e32 v[52:53], 0
	v_mov_b64_e32 v[54:55], 0
	v_mov_b64_e32 v[60:61], 0
	v_mov_b64_e32 v[62:63], 0
	v_mov_b64_e32 v[64:65], 0
	v_mov_b64_e32 v[66:67], 0
	v_mov_b64_e32 v[72:73], 0
	v_mov_b64_e32 v[74:75], 0
	v_mov_b64_e32 v[80:81], 0
	v_mov_b64_e32 v[82:83], 0
	v_mov_b64_e32 v[88:89], 0
	v_mov_b64_e32 v[90:91], 0
	v_mov_b64_e32 v[96:97], 0
	v_mov_b64_e32 v[98:99], 0
	v_mov_b64_e32 v[104:105], 0
	v_mov_b64_e32 v[106:107], 0
	v_mov_b64_e32 v[112:113], 0
	v_mov_b64_e32 v[114:115], 0
	v_mov_b64_e32 v[120:121], 0
	v_mov_b64_e32 v[122:123], 0
	v_mov_b64_e32 v[68:69], 0
	v_mov_b64_e32 v[70:71], 0
	v_mov_b64_e32 v[76:77], 0
	v_mov_b64_e32 v[78:79], 0
	v_mov_b64_e32 v[84:85], 0
	v_mov_b64_e32 v[86:87], 0
	v_mov_b64_e32 v[92:93], 0
	v_mov_b64_e32 v[94:95], 0
	v_mov_b64_e32 v[100:101], 0
	v_mov_b64_e32 v[102:103], 0
	v_mov_b64_e32 v[108:109], 0
	v_mov_b64_e32 v[110:111], 0
	v_mov_b64_e32 v[116:117], 0
	v_mov_b64_e32 v[118:119], 0
	v_mov_b64_e32 v[124:125], 0
	v_mov_b64_e32 v[126:127], 0

;     __device__ __forceinline__ int nt_of(const Unit& u) const { return (u.pm >> 12) ? ktper : kt; }
; template <class Epi, class Sched, bool ALIGN_EPI = false, bool SP2 = false>
; __device__ __forceinline__ void gemm_phase(PG8_LAS unsigned char* lds, const Gemm g, const Sched& S, const Epi& E, int wave_s_) {
;     ...
;         const int nt = S.nt_of(cur);
;         for (int t = 0; t < nt; t += 2) {
;     ...
; #pragma unroll
;         for (int a = 0; a < 2; ++a)
; #pragma unroll
;             for (int b = 0; b < 2; ++b)
; #pragma unroll
;                 for (int m = 0; m < 4; ++m)
; #pragma unroll
;                     for (int n = 0; n < 2; ++n) acc[a][b][m][n] = (f32x4){0.f, 0.f, 0.f, 0.f};
.LBB0_297:
	s_cmpk_gt_u32 s57, 0xfff
	s_cselect_b64 s[30:31], -1, 0
	s_cmpk_lt_u32 s57, 0x1000
	s_cselect_b64 s[8:9], -1, 0
	s_and_b64 s[34:35], s[8:9], exec
	s_cselect_b32 s59, 44, 4
	s_add_i32 s60, s59, -2
	s_add_u32 s61, s12, 0x100
	v_mov_b32_e32 v0, 0
	s_addc_u32 s62, s13, 0
	s_mov_b32 s34, 0
	v_mov_b32_e32 v1, v0
	v_mov_b64_e32 v[2:3], 0
	v_mov_b64_e32 v[4:5], 0
	v_mov_b64_e32 v[6:7], 0
	v_mov_b64_e32 v[12:13], 0
	v_mov_b64_e32 v[14:15], 0
	v_mov_b64_e32 v[20:21], 0
	v_mov_b64_e32 v[22:23], 0
	v_mov_b64_e32 v[32:33], 0
	v_mov_b64_e32 v[34:35], 0
	v_mov_b64_e32 v[36:37], 0
	v_mov_b64_e32 v[38:39], 0
	v_mov_b64_e32 v[44:45], 0
	v_mov_b64_e32 v[46:47], 0
	v_mov_b64_e32 v[52:53], 0
	v_mov_b64_e32 v[54:55], 0
	v_mov_b64_e32 v[8:9], 0
	v_mov_b64_e32 v[10:11], 0
	v_mov_b64_e32 v[16:17], 0
	v_mov_b64_e32 v[18:19], 0
	v_mov_b64_e32 v[24:25], 0
	v_mov_b64_e32 v[26:27], 0
	v_mov_b64_e32 v[28:29], 0
	v_mov_b64_e32 v[30:31], 0
	v_mov_b64_e32 v[40:41], 0
	v_mov_b64_e32 v[42:43], 0
	v_mov_b64_e32 v[48:49], 0
	v_mov_b64_e32 v[50:51], 0
	v_mov_b64_e32 v[56:57], 0
	v_mov_b64_e32 v[58:59], 0
	v_mov_b64_e32 v[60:61], 0
	v_mov_b64_e32 v[62:63], 0
	v_mov_b64_e32 v[72:73], 0
	v_mov_b64_e32 v[74:75], 0
	v_mov_b64_e32 v[84:85], 0
	v_mov_b64_e32 v[86:87], 0
	v_mov_b64_e32 v[108:109], 0
	v_mov_b64_e32 v[110:111], 0
	v_mov_b64_e32 v[116:117], 0
	v_mov_b64_e32 v[118:119], 0
	v_mov_b64_e32 v[128:129], 0
	v_mov_b64_e32 v[130:131], 0
	v_mov_b64_e32 v[132:133], 0
	v_mov_b64_e32 v[134:135], 0
	v_mov_b64_e32 v[140:141], 0
	v_mov_b64_e32 v[142:143], 0
	v_mov_b64_e32 v[148:149], 0
	v_mov_b64_e32 v[150:151], 0
	v_mov_b64_e32 v[104:105], 0
	v_mov_b64_e32 v[106:107], 0
	v_mov_b64_e32 v[112:113], 0
	v_mov_b64_e32 v[114:115], 0
	v_mov_b64_e32 v[120:121], 0
	v_mov_b64_e32 v[122:123], 0
	v_mov_b64_e32 v[124:125], 0
	v_mov_b64_e32 v[126:127], 0
	v_mov_b64_e32 v[136:137], 0
	v_mov_b64_e32 v[138:139], 0
	v_mov_b64_e32 v[144:145], 0
	v_mov_b64_e32 v[146:147], 0
	v_mov_b64_e32 v[152:153], 0
	v_mov_b64_e32 v[154:155], 0
	v_mov_b64_e32 v[156:157], 0
	v_mov_b64_e32 v[158:159], 0

; __device__ __forceinline__ void zero16(void* p_, int n16, int gtid, int gthreads) { unsigned z = 0u; asm volatile("" : "+v"(z)); for (int i = gtid; i < n16; i += gthreads) ((u32x4*)p_)[i] = (u32x4){z, z, z, z}; }
; __global__ void __launch_bounds__(NT, 2) fwd_megakernel(Args a_unused) {
;     ...
;                 zero16(ws + WS_KA + (size_t)KA_ROWS * 512 * 2, 64 * 512 * 2 / 16, gtid, gthreads); zero16(ws + WS_VA + (size_t)KA_ROWS * 512 * 2, 64 * 512 * 2 / 16, gtid, gthreads);
;                 zero16(ws + WS_KB + (size_t)KB_ROWS * 128 * 2, 64 * 128 * 2 / 16, gtid, gthreads); zero16(ws + WS_VB + (size_t)KB_ROWS * 128 * 2, 64 * 128 * 2 / 16, gtid, gthreads);
.LBB0_474:
	s_or_b64 exec, exec, s[10:11]
	v_mov_b32_e32 v0, v197
	v_cmp_gt_i32_e32 vcc, s2, v4
	v_ashrrev_i32_e32 v5, 31, v4
	s_and_saveexec_b64 s[10:11], vcc
	s_movk_i32 s1, 0xfff
	s_cbranch_execz .LBB0_477
	s_waitcnt lgkmcnt(0)
	v_lshl_add_u64 v[6:7], v[4:5], 4, s[8:9]
	s_mov_b64 s[4:5], 0xfc38000
	s_ashr_i32 s7, s6, 31
	v_mov_b32_e32 v1, v0
	v_mov_b64_e32 v[2:3], 0
	v_lshl_add_u64 v[6:7], v[6:7], 0, s[4:5]
	s_lshl_b64 s[12:13], s[6:7], 4
	s_mov_b64 s[14:15], 0
	v_mov_b32_e32 v8, v4

; __device__ __forceinline__ void zero16(void* p_, int n16, int gtid, int gthreads) { unsigned z = 0u; asm volatile("" : "+v"(z)); for (int i = gtid; i < n16; i += gthreads) ((u32x4*)p_)[i] = (u32x4){z, z, z, z}; }
; __global__ void __launch_bounds__(NT, 2) fwd_megakernel(Args a_unused) {
;     ...
;                 zero16(ws + WS_KA + (size_t)KA_ROWS * 512 * 2, 64 * 512 * 2 / 16, gtid, gthreads); zero16(ws + WS_VA + (size_t)KA_ROWS * 512 * 2, 64 * 512 * 2 / 16, gtid, gthreads);
;                 zero16(ws + WS_KB + (size_t)KB_ROWS * 128 * 2, 64 * 128 * 2 / 16, gtid, gthreads); zero16(ws + WS_VB + (size_t)KB_ROWS * 128 * 2, 64 * 128 * 2 / 16, gtid, gthreads);
.LBB0_477:
	s_or_b64 exec, exec, s[10:11]
	s_movk_i32 s2, 0x3ff
	v_mov_b32_e32 v0, v197
	s_and_saveexec_b64 s[4:5], vcc
	s_cbranch_execz .LBB0_480
	s_waitcnt lgkmcnt(0)
	v_lshl_add_u64 v[6:7], v[4:5], 4, s[8:9]
	s_mov_b64 s[10:11], 0x124c8000
	s_ashr_i32 s7, s6, 31
	v_mov_b32_e32 v1, v0
	v_mov_b64_e32 v[2:3], 0
	v_lshl_add_u64 v[6:7], v[6:7], 0, s[10:11]
	s_lshl_b64 s[10:11], s[6:7], 4
	s_mov_b64 s[12:13], 0
	v_mov_b32_e32 v8, v4

; __device__ __forceinline__ void zero16(void* p_, int n16, int gtid, int gthreads) { unsigned z = 0u; asm volatile("" : "+v"(z)); for (int i = gtid; i < n16; i += gthreads) ((u32x4*)p_)[i] = (u32x4){z, z, z, z}; }
; __global__ void __launch_bounds__(NT, 2) fwd_megakernel(Args a_unused) {
;     ...
;                 zero16(ws + WS_KA + (size_t)KA_ROWS * 512 * 2, 64 * 512 * 2 / 16, gtid, gthreads); zero16(ws + WS_VA + (size_t)KA_ROWS * 512 * 2, 64 * 512 * 2 / 16, gtid, gthreads);
;                 zero16(ws + WS_KB + (size_t)KB_ROWS * 128 * 2, 64 * 128 * 2 / 16, gtid, gthreads); zero16(ws + WS_VB + (size_t)KB_ROWS * 128 * 2, 64 * 128 * 2 / 16, gtid, gthreads);
.LBB0_480:
	s_or_b64 exec, exec, s[4:5]
	s_movk_i32 s1, 0x400
	v_mov_b32_e32 v0, v197
	v_cmp_gt_i32_e32 vcc, s1, v4
	s_and_saveexec_b64 s[10:11], vcc
	s_cbranch_execz .LBB0_483
	s_waitcnt lgkmcnt(0)
	v_lshl_add_u64 v[6:7], v[4:5], 4, s[8:9]
	s_mov_b64 s[4:5], 0x12d78000
	s_ashr_i32 s7, s6, 31
	v_mov_b32_e32 v1, v0
	v_mov_b64_e32 v[2:3], 0
	v_lshl_add_u64 v[6:7], v[6:7], 0, s[4:5]
	s_lshl_b64 s[12:13], s[6:7], 4
	s_mov_b64 s[14:15], 0
	v_mov_b32_e32 v8, v4

; __device__ __forceinline__ void zero16(void* p_, int n16, int gtid, int gthreads) { unsigned z = 0u; asm volatile("" : "+v"(z)); for (int i = gtid; i < n16; i += gthreads) ((u32x4*)p_)[i] = (u32x4){z, z, z, z}; }
; __global__ void __launch_bounds__(NT, 2) fwd_megakernel(Args a_unused) {
;     ...
;                 zero16(ws + WS_KA + (size_t)KA_ROWS * 512 * 2, 64 * 512 * 2 / 16, gtid, gthreads); zero16(ws + WS_VA + (size_t)KA_ROWS * 512 * 2, 64 * 512 * 2 / 16, gtid, gthreads);
;                 zero16(ws + WS_KB + (size_t)KB_ROWS * 128 * 2, 64 * 128 * 2 / 16, gtid, gthreads); zero16(ws + WS_VB + (size_t)KB_ROWS * 128 * 2, 64 * 128 * 2 / 16, gtid, gthreads);
.LBB0_483:
	s_or_b64 exec, exec, s[10:11]
	v_mov_b32_e32 v0, v197
	s_and_saveexec_b64 s[4:5], vcc
	s_cbranch_execz .LBB0_486
	s_waitcnt lgkmcnt(0)
	v_lshl_add_u64 v[6:7], v[4:5], 4, s[8:9]
	s_mov_b64 s[8:9], 0x1361c000
	s_ashr_i32 s7, s6, 31
	v_mov_b32_e32 v1, v0
	v_mov_b64_e32 v[2:3], 0
	v_lshl_add_u64 v[6:7], v[6:7], 0, s[8:9]
	s_lshl_b64 s[8:9], s[6:7], 4
	s_mov_b64 s[10:11], 0

; template <class Epi, class Sched, bool ALIGN_EPI = false, bool SP2 = false>
; __device__ __forceinline__ void gemm_phase(PG8_LAS unsigned char* lds, const Gemm g, const Sched& S, const Epi& E, int wave_s_) {
;     ...
; #pragma unroll
;         for (int a = 0; a < 2; ++a)
; #pragma unroll
;             for (int b = 0; b < 2; ++b)
; #pragma unroll
;                 for (int m = 0; m < 4; ++m)
; #pragma unroll
;                     for (int n = 0; n < 2; ++n) acc[a][b][m][n] = (f32x4){0.f, 0.f, 0.f, 0.f};
.LBB0_561:
	s_add_u32 s6, s12, 0x40080
	s_addc_u32 s7, s13, 0
	s_add_u32 s9, s10, 0x100
	v_mov_b32_e32 v0, 0
	s_addc_u32 s14, s11, 0
	s_mov_b32 s15, -2
	v_mov_b32_e32 v1, v0
	v_mov_b64_e32 v[2:3], 0
	v_mov_b64_e32 v[4:5], 0
	v_mov_b64_e32 v[6:7], 0
	v_mov_b64_e32 v[8:9], 0
	v_mov_b64_e32 v[10:11], 0
	v_mov_b64_e32 v[12:13], 0
	v_mov_b64_e32 v[14:15], 0
	v_mov_b64_e32 v[16:17], 0
	v_mov_b64_e32 v[18:19], 0
	v_mov_b64_e32 v[20:21], 0
	v_mov_b64_e32 v[22:23], 0
	v_mov_b64_e32 v[24:25], 0
	v_mov_b64_e32 v[26:27], 0
	v_mov_b64_e32 v[28:29], 0
	v_mov_b64_e32 v[30:31], 0
	v_mov_b64_e32 v[64:65], 0
	v_mov_b64_e32 v[66:67], 0
	v_mov_b64_e32 v[68:69], 0
	v_mov_b64_e32 v[70:71], 0
	v_mov_b64_e32 v[72:73], 0
	v_mov_b64_e32 v[74:75], 0
	v_mov_b64_e32 v[76:77], 0
	v_mov_b64_e32 v[78:79], 0
	v_mov_b64_e32 v[80:81], 0
	v_mov_b64_e32 v[82:83], 0
	v_mov_b64_e32 v[84:85], 0
	v_mov_b64_e32 v[86:87], 0
	v_mov_b64_e32 v[88:89], 0
	v_mov_b64_e32 v[90:91], 0
	v_mov_b64_e32 v[92:93], 0
	v_mov_b64_e32 v[94:95], 0
	v_mov_b64_e32 v[32:33], 0
	v_mov_b64_e32 v[34:35], 0
	v_mov_b64_e32 v[36:37], 0
	v_mov_b64_e32 v[38:39], 0
	v_mov_b64_e32 v[40:41], 0
	v_mov_b64_e32 v[42:43], 0
	v_mov_b64_e32 v[44:45], 0
	v_mov_b64_e32 v[46:47], 0
	v_mov_b64_e32 v[48:49], 0
	v_mov_b64_e32 v[50:51], 0
	v_mov_b64_e32 v[52:53], 0
	v_mov_b64_e32 v[54:55], 0
	v_mov_b64_e32 v[56:57], 0
	v_mov_b64_e32 v[58:59], 0
	v_mov_b64_e32 v[60:61], 0
	v_mov_b64_e32 v[62:63], 0
	v_mov_b64_e32 v[96:97], 0
	v_mov_b64_e32 v[98:99], 0
	v_mov_b64_e32 v[100:101], 0
	v_mov_b64_e32 v[102:103], 0
	v_mov_b64_e32 v[104:105], 0
	v_mov_b64_e32 v[106:107], 0
	v_mov_b64_e32 v[108:109], 0
	v_mov_b64_e32 v[110:111], 0
	v_mov_b64_e32 v[112:113], 0
	v_mov_b64_e32 v[114:115], 0
	v_mov_b64_e32 v[116:117], 0
	v_mov_b64_e32 v[118:119], 0
	v_mov_b64_e32 v[120:121], 0
	v_mov_b64_e32 v[122:123], 0
	v_mov_b64_e32 v[124:125], 0
	v_mov_b64_e32 v[126:127], 0

; template <int DQ, bool BIAS>
; __device__ __forceinline__ void attn_item_l0(const AttnItem& A, LAS unsigned char* lds, int wave_s_) {
;     ...
;     const int wlo = max(A.wlo0 + w * A.wstep_lo, A.t_lo), whi = min(A.whi0 + w * A.wstep, A.t_hi);
;     const int qrow = A.q_row0 + 64 * w;
;     bf16x8 qf[2][NKK];
; #pragma unroll
;     for (int qb = 0; qb < 2; ++qb)
; #pragma unroll
;         for (int kk = 0; kk < NKK; ++kk) qf[qb][kk] = *(const bf16x8*)(A.Q + (size_t)((wlo <= whi ? qrow : A.q_row0) + 32 * qb + r32) * A.q_stride + 16 * kk + 8 * hi);
;     if (DQ == 96) {
; #pragma unroll
;         for (int qb = 0; qb < 2; ++qb) {
;             const int row = (wlo <= whi ? qrow : A.q_row0) + 32 * qb + r32; const int pos = row < NPROMPT ? (row & (SEQ - 1)) : PAST + ((row - NPROMPT) & 31);
;             const float* rp = A.rope + (size_t)pos * 32 + 8 * hi;
;             const f32x4 c0 = *(const f32x4*)rp, c1 = *(const f32x4*)(rp + 4), s0 = *(const f32x4*)(rp + 16), s1 = *(const f32x4*)(rp + 20);
;             u32x4 w1, w2;
; #pragma unroll
;             for (int jp = 0; jp < 4; ++jp) {
;                 float o1[2], o2[2];
; #pragma unroll
;                 for (int e = 0; e < 2; ++e) { const int j = 2 * jp + e;
;                     const float x1 = __builtin_bit_cast(float, (unsigned)(unsigned short)qf[qb][NKK - 2][j] << 16), x2 = __builtin_bit_cast(float, (unsigned)(unsigned short)qf[qb][NKK - 1][j] << 16);
;                     const float c = j < 4 ? c0[j & 3] : c1[j & 3], s = j < 4 ? s0[j & 3] : s1[j & 3];
;                     o1[e] = x1 * c - x2 * s; o2[e] = x1 * s + x2 * c; }
;                 w1[jp] = pk2(o1[0], o1[1]); w2[jp] = pk2(o2[0], o2[1]);
;             }
;             qf[qb][NKK - 2] = __builtin_bit_cast(bf16x8, w1); qf[qb][NKK - 1] = __builtin_bit_cast(bf16x8, w2);
;         }
;     }
;     f32x16 o[2][2];
; #pragma unroll
;     for (int d = 0; d < 2; ++d)
; #pragma unroll
;         for (int qb = 0; qb < 2; ++qb)
; #pragma unroll
;             for (int i = 0; i < 16; ++i) o[d][qb][i] = 0.f;
;     float mrun[2] = {A.m0, A.m0}, lrun[2] = {hi == 0 ? A.l0 : 0.f, hi == 0 ? A.l0 : 0.f};
;     const int lkey = tid >> 3, lpc = tid & 7, l2key = tid >> 2, l2pc = tid & 3;
;     u32x4 kreg, k2reg, vreg;
;     auto gload = [&](int t) {
;         const size_t row = (size_t)(A.k_row0 + 64 * t);
.LBB0_1033:
	s_or_b64 exec, exec, s[10:11]
	s_ashr_i32 s6, s24, 6
	s_mul_i32 s7, s6, s21
	s_mul_i32 s6, s6, s20
	s_add_i32 s6, s6, s22
	s_add_i32 s7, s7, s23
	s_min_i32 s71, s6, s90
	s_and_b32 s6, s24, 0xffffffc0
	s_max_i32 s70, s7, s91
	s_add_i32 s89, s6, s19
	s_cmp_le_i32 s70, s71
	s_cselect_b64 s[92:93], -1, 0
	s_cmp_gt_i32 s70, s71
	v_and_b32_e32 v245, 31, v4
	s_cselect_b32 s7, s19, s89
	v_add_u32_e32 v6, s7, v245
	v_ashrrev_i32_e32 v0, 3, v0
	s_lshl_b32 s7, s91, 6
	v_bfe_u32 v5, v4, 5, 1
	s_add_i32 s72, s18, s7
	v_ashrrev_i32_e32 v1, 31, v0
	v_lshlrev_b32_e32 v2, 4, v5
	v_mov_b32_e32 v3, v197
	v_ashrrev_i32_e32 v7, 31, v6
	v_lshl_add_u64 v[12:13], v[0:1], 0, s[72:73]
	v_lshl_add_u64 v[8:9], s[8:9], 0, v[2:3]
	v_lshlrev_b64 v[10:11], 11, v[6:7]
	v_mul_lo_u32 v7, v13, s4
	v_mul_lo_u32 v14, v12, s5
	v_mad_u64_u32 v[12:13], s[8:9], v12, s4, 0
	v_add3_u32 v13, v13, v14, v7
	v_add_u32_e32 v6, 32, v6
	v_and_b32_e32 v3, 7, v4
	v_lshlrev_b64 v[12:13], 1, v[12:13]
	v_ashrrev_i32_e32 v7, 31, v6
	v_lshl_add_u64 v[14:15], s[74:75], 0, v[12:13]
	v_lshlrev_b32_e32 v196, 4, v3
	v_lshl_add_u64 v[12:13], s[82:83], 0, v[12:13]
	v_lshlrev_b64 v[6:7], 11, v[6:7]
	v_lshl_add_u64 v[14:15], v[14:15], 0, v[196:197]
	v_lshl_add_u64 v[12:13], v[12:13], 0, v[196:197]
	v_lshl_add_u64 v[6:7], v[8:9], 0, v[6:7]
	v_lshl_add_u64 v[10:11], v[8:9], 0, v[10:11]
	global_load_dwordx4 v[128:131], v[14:15], off
	global_load_dwordx4 v[148:151], v[12:13], off
	global_load_dwordx4 v[132:135], v[10:11], off
	global_load_dwordx4 v[136:139], v[10:11], off offset:32
	global_load_dwordx4 v[140:143], v[10:11], off offset:64
	global_load_dwordx4 v[144:147], v[10:11], off offset:96
	global_load_dwordx4 v[152:155], v[6:7], off
	global_load_dwordx4 v[156:159], v[6:7], off offset:32
	global_load_dwordx4 v[160:163], v[6:7], off offset:64
	global_load_dwordx4 v[164:167], v[6:7], off offset:96
	v_and_b32_e32 v4, 63, v4
	v_mov_b32_e32 v6, s16
	v_lshlrev_b32_e32 v170, 3, v5
	v_cmp_gt_u32_e32 vcc, 32, v4
	v_lshlrev_b32_e32 v246, 2, v5
	v_lshlrev_b32_e32 v5, 2, v4
	v_add_u32_e32 v4, 0, v196
	s_movk_i32 s8, 0xd0
	v_cndmask_b32_e32 v168, 0, v6, vcc
	v_mul_u32_u24_e32 v3, 0x430, v3
	v_lshlrev_b32_e32 v6, 1, v0
	v_mad_u64_u32 v[172:173], s[8:9], v0, s8, v[4:5]
	v_mov_b32_e32 v47, 0
	v_add3_u32 v171, v4, v3, v6
	s_cmp_le_u32 s91, s90
	v_xor_b32_e32 v173, 0x80, v5
	s_waitcnt vmcnt(9)
	ds_write_b128 v172, v[128:131]
	s_waitcnt vmcnt(8)
	ds_write_b16 v171, v148 offset:26624
	ds_write_b16_d16_hi v171, v148 offset:26760
	ds_write_b16 v171, v149 offset:26896
	ds_write_b16_d16_hi v171, v149 offset:27032
	ds_write_b16 v171, v150 offset:27168
	ds_write_b16_d16_hi v171, v150 offset:27304
	ds_write_b16 v171, v151 offset:27440
	ds_write_b16_d16_hi v171, v151 offset:27576
	s_waitcnt lgkmcnt(0)
	s_barrier
	s_cbranch_scc0 .LBB0_1042
	s_add_i32 s17, s17, s6
	v_add_u32_e32 v247, 0, v2
	v_lshl_or_b32 v2, s91, 8, v2
	v_add_lshl_u32 v3, s17, v245, 2
	s_add_i32 s72, s72, 64
	v_sub_u32_e32 v2, v2, v3
	v_readlane_b32 s6, v255, 3
	s_lshl_b32 s8, s4, 1
	v_lshl_add_u64 v[0:1], v[0:1], 0, s[72:73]
	v_add_u32_e32 v251, s6, v2
	v_add3_u32 v252, s7, 59, v246
	v_mad_u64_u32 v[174:175], s[6:7], s8, v0, v[196:197]
	s_lshr_b64 s[6:7], s[4:5], 31
	v_mul_lo_u32 v1, s8, v1
	v_mul_lo_u32 v0, s6, v0
	v_add3_u32 v175, v0, v175, v1
	v_mov_b32_e32 v0, 0
	v_sub_u32_e32 v248, v247, v170
	v_mul_u32_u24_e32 v249, 0xd0, v245
	v_mul_u32_u24_e32 v250, 0x88, v245
	s_lshl_b64 s[94:95], s[4:5], 7
	s_mov_b32 s72, 0
	v_mov_b32_e32 v178, v179
	v_mov_b32_e32 v1, v0
	v_mov_b64_e32 v[2:3], 0
	v_mov_b64_e32 v[4:5], 0
	v_mov_b64_e32 v[6:7], 0
	v_mov_b64_e32 v[8:9], 0
	v_mov_b64_e32 v[10:11], 0
	v_mov_b64_e32 v[12:13], 0
	v_mov_b64_e32 v[14:15], 0
	v_mov_b64_e32 v[48:49], 0
	v_mov_b64_e32 v[50:51], 0
	v_mov_b64_e32 v[52:53], 0
	v_mov_b64_e32 v[54:55], 0
	v_mov_b64_e32 v[56:57], 0
	v_mov_b64_e32 v[58:59], 0
	v_mov_b64_e32 v[60:61], 0
	v_mov_b64_e32 v[62:63], 0
	v_mov_b64_e32 v[16:17], 0
	v_mov_b64_e32 v[18:19], 0
	v_mov_b64_e32 v[20:21], 0
	v_mov_b64_e32 v[22:23], 0
	v_mov_b64_e32 v[24:25], 0
	v_mov_b64_e32 v[26:27], 0
	v_mov_b64_e32 v[28:29], 0
	v_mov_b64_e32 v[30:31], 0
	v_mov_b64_e32 v[32:33], 0
	v_mov_b64_e32 v[34:35], 0
	v_mov_b64_e32 v[36:37], 0
	v_mov_b64_e32 v[38:39], 0
	v_mov_b64_e32 v[40:41], 0
	v_mov_b64_e32 v[42:43], 0
	v_mov_b64_e32 v[44:45], 0
	v_mov_b64_e32 v[46:47], 0
	v_mov_b32_e32 v169, v168
	s_waitcnt vmcnt(0)
	s_branch .LBB0_1036

; __device__ __forceinline__ void zero16(void* p_, int n16, int gtid, int gthreads) { unsigned z = 0u; asm volatile("" : "+v"(z)); for (int i = gtid; i < n16; i += gthreads) ((u32x4*)p_)[i] = (u32x4){z, z, z, z}; }
; __device__ __forceinline__ void prologue_l1(ArgsP a, int wave_s_) {
;     ...
;     zero16(a->ws + WS_KR + (size_t)RKV * 32 * 2, 64 * 32 * 2 / 16, gtid, gthreads);
.LBB0_1108:
	s_or_b64 exec, exec, s[8:9]
	s_movk_i32 s1, 0x100
	v_mov_b32_e32 v0, v197
	v_cmp_gt_i32_e32 vcc, s1, v4
	s_and_saveexec_b64 s[8:9], vcc
	s_cbranch_execz .LBB0_1111
	v_ashrrev_i32_e32 v5, 31, v4
	s_waitcnt lgkmcnt(0)
	v_lshl_add_u64 v[6:7], v[4:5], 4, s[6:7]
	s_mov_b64 s[6:7], 0xc640000
	s_ashr_i32 s5, s4, 31
	v_mov_b32_e32 v1, v0
	v_mov_b64_e32 v[2:3], 0
	v_lshl_add_u64 v[6:7], v[6:7], 0, s[6:7]
	s_lshl_b64 s[6:7], s[4:5], 4
	s_mov_b64 s[10:11], 0

; template <class Epi, class Sched, bool ALIGN_EPI = false, bool SP2 = false>
; __device__ __forceinline__ void gemm_phase(PG8_LAS unsigned char* lds, const Gemm g, const Sched& S, const Epi& E, int wave_s_) {
;     ...
; #pragma unroll
;         for (int a = 0; a < 2; ++a)
; #pragma unroll
;             for (int b = 0; b < 2; ++b)
; #pragma unroll
;                 for (int m = 0; m < 4; ++m)
; #pragma unroll
;                     for (int n = 0; n < 2; ++n) acc[a][b][m][n] = (f32x4){0.f, 0.f, 0.f, 0.f};
.LBB0_1184:
	s_add_u32 s18, s18, 0x40080
	s_addc_u32 s19, s19, 0
	s_add_u32 s15, s20, 0x100
	v_mov_b32_e32 v0, 0
	s_addc_u32 s44, s21, 0
	s_mov_b32 s45, -2
	v_mov_b32_e32 v1, v0
	v_mov_b64_e32 v[2:3], 0
	v_mov_b64_e32 v[4:5], 0
	v_mov_b64_e32 v[6:7], 0
	v_mov_b64_e32 v[8:9], 0
	v_mov_b64_e32 v[10:11], 0
	v_mov_b64_e32 v[12:13], 0
	v_mov_b64_e32 v[14:15], 0
	v_mov_b64_e32 v[16:17], 0
	v_mov_b64_e32 v[18:19], 0
	v_mov_b64_e32 v[24:25], 0
	v_mov_b64_e32 v[26:27], 0
	v_mov_b64_e32 v[32:33], 0
	v_mov_b64_e32 v[34:35], 0
	v_mov_b64_e32 v[40:41], 0
	v_mov_b64_e32 v[42:43], 0
	v_mov_b64_e32 v[20:21], 0
	v_mov_b64_e32 v[22:23], 0
	v_mov_b64_e32 v[28:29], 0
	v_mov_b64_e32 v[30:31], 0
	v_mov_b64_e32 v[36:37], 0
	v_mov_b64_e32 v[38:39], 0
	v_mov_b64_e32 v[44:45], 0
	v_mov_b64_e32 v[46:47], 0
	v_mov_b64_e32 v[48:49], 0
	v_mov_b64_e32 v[50:51], 0
	v_mov_b64_e32 v[52:53], 0
	v_mov_b64_e32 v[54:55], 0
	v_mov_b64_e32 v[56:57], 0
	v_mov_b64_e32 v[58:59], 0
	v_mov_b64_e32 v[60:61], 0
	v_mov_b64_e32 v[62:63], 0
	v_mov_b64_e32 v[64:65], 0
	v_mov_b64_e32 v[66:67], 0
	v_mov_b64_e32 v[68:69], 0
	v_mov_b64_e32 v[70:71], 0
	v_mov_b64_e32 v[72:73], 0
	v_mov_b64_e32 v[74:75], 0
	v_mov_b64_e32 v[76:77], 0
	v_mov_b64_e32 v[78:79], 0
	v_mov_b64_e32 v[80:81], 0
	v_mov_b64_e32 v[82:83], 0
	v_mov_b64_e32 v[88:89], 0
	v_mov_b64_e32 v[90:91], 0
	v_mov_b64_e32 v[96:97], 0
	v_mov_b64_e32 v[98:99], 0
	v_mov_b64_e32 v[104:105], 0
	v_mov_b64_e32 v[106:107], 0
	v_mov_b64_e32 v[84:85], 0
	v_mov_b64_e32 v[86:87], 0
	v_mov_b64_e32 v[92:93], 0
	v_mov_b64_e32 v[94:95], 0
	v_mov_b64_e32 v[100:101], 0
	v_mov_b64_e32 v[102:103], 0
	v_mov_b64_e32 v[108:109], 0
	v_mov_b64_e32 v[110:111], 0
	v_mov_b64_e32 v[112:113], 0
	v_mov_b64_e32 v[114:115], 0
	v_mov_b64_e32 v[116:117], 0
	v_mov_b64_e32 v[118:119], 0
	v_mov_b64_e32 v[120:121], 0
	v_mov_b64_e32 v[122:123], 0
	v_mov_b64_e32 v[124:125], 0
	v_mov_b64_e32 v[126:127], 0

; __device__ __forceinline__ void zero16(void* p_, int n16, int gtid, int gthreads) { unsigned z = 0u; asm volatile("" : "+v"(z)); for (int i = gtid; i < n16; i += gthreads) ((u32x4*)p_)[i] = (u32x4){z, z, z, z}; }
; __global__ void __launch_bounds__(NT, 2) fwd_megakernel(Args a_unused) {
;     ...
;                 zero16(ws + WS_KC + (size_t)RKV * 1024 * 2, 64 * 1024 * 2 / 16, gtid, gthreads); zero16(ws + WS_VC + (size_t)RKV * 1024 * 2, 64 * 1024 * 2 / 16, gtid, gthreads); }
.LBB0_1311:
	s_or_b64 exec, exec, s[4:5]
	s_mov_b64 s[4:5], s[82:83]
	s_mov_b32 s1, s84
	s_waitcnt lgkmcnt(0)
	s_barrier
	s_load_dwordx2 s[8:9], s[4:5], 0xe8
	v_mbcnt_lo_u32_b32 v0, -1, 0
	v_mbcnt_hi_u32_b32 v0, -1, v0
	s_nop 0
	v_or_b32_e32 v0, s96, v0
	v_lshl_add_u32 v4, s1, 9, v0
	s_mov_b32 s1, s94
	s_lshl_b32 s6, s1, 9
	s_movk_i32 s1, 0x2000
	v_mov_b32_e32 v0, v197
	v_cmp_gt_i32_e32 vcc, s1, v4
	v_ashrrev_i32_e32 v5, 31, v4
	s_and_saveexec_b64 s[10:11], vcc
	s_cbranch_execz .LBB0_1314
	s_waitcnt lgkmcnt(0)
	v_lshl_add_u64 v[6:7], v[4:5], 4, s[8:9]
	s_mov_b64 s[4:5], 0x188f1000
	s_ashr_i32 s7, s6, 31
	v_mov_b32_e32 v1, v0
	v_mov_b64_e32 v[2:3], 0
	v_lshl_add_u64 v[6:7], v[6:7], 0, s[4:5]
	s_lshl_b64 s[12:13], s[6:7], 4
	s_mov_b64 s[14:15], 0
	v_mov_b32_e32 v8, v4

; __device__ __forceinline__ void zero16(void* p_, int n16, int gtid, int gthreads) { unsigned z = 0u; asm volatile("" : "+v"(z)); for (int i = gtid; i < n16; i += gthreads) ((u32x4*)p_)[i] = (u32x4){z, z, z, z}; }
; __global__ void __launch_bounds__(NT, 2) fwd_megakernel(Args a_unused) {
;     ...
;                 zero16(ws + WS_KC + (size_t)RKV * 1024 * 2, 64 * 1024 * 2 / 16, gtid, gthreads); zero16(ws + WS_VC + (size_t)RKV * 1024 * 2, 64 * 1024 * 2 / 16, gtid, gthreads); }
.LBB0_1314:
	s_or_b64 exec, exec, s[10:11]
	v_mov_b32_e32 v0, v197
	s_and_saveexec_b64 s[4:5], vcc
	s_cbranch_execz .LBB0_1317
	s_waitcnt lgkmcnt(0)
	v_lshl_add_u64 v[6:7], v[4:5], 4, s[8:9]
	s_mov_b64 s[8:9], 0x1ea71000
	s_ashr_i32 s7, s6, 31
	v_mov_b32_e32 v1, v0
	v_mov_b64_e32 v[2:3], 0
	v_lshl_add_u64 v[6:7], v[6:7], 0, s[8:9]
	s_lshl_b64 s[8:9], s[6:7], 4
	s_mov_b64 s[10:11], 0

; template <class Epi, class Sched, bool ALIGN_EPI = false, bool SP2 = false>
; __device__ __forceinline__ void gemm_phase(PG8_LAS unsigned char* lds, const Gemm g, const Sched& S, const Epi& E, int wave_s_) {
;     ...
; #pragma unroll
;         for (int a = 0; a < 2; ++a)
; #pragma unroll
;             for (int b = 0; b < 2; ++b)
; #pragma unroll
;                 for (int m = 0; m < 4; ++m)
; #pragma unroll
;                     for (int n = 0; n < 2; ++n) acc[a][b][m][n] = (f32x4){0.f, 0.f, 0.f, 0.f};
.LBB0_1337:
	s_add_u32 s45, s18, 0x100
	v_mov_b32_e32 v0, 0
	s_addc_u32 s46, s19, 0
	s_mov_b32 s47, -2
	v_mov_b32_e32 v1, v0
	v_mov_b64_e32 v[2:3], 0
	v_mov_b64_e32 v[4:5], 0
	v_mov_b64_e32 v[6:7], 0
	v_mov_b64_e32 v[8:9], 0
	v_mov_b64_e32 v[10:11], 0
	v_mov_b64_e32 v[16:17], 0
	v_mov_b64_e32 v[18:19], 0
	v_mov_b64_e32 v[24:25], 0
	v_mov_b64_e32 v[26:27], 0
	v_mov_b64_e32 v[32:33], 0
	v_mov_b64_e32 v[34:35], 0
	v_mov_b64_e32 v[40:41], 0
	v_mov_b64_e32 v[42:43], 0
	v_mov_b64_e32 v[48:49], 0
	v_mov_b64_e32 v[50:51], 0
	v_mov_b64_e32 v[12:13], 0
	v_mov_b64_e32 v[14:15], 0
	v_mov_b64_e32 v[20:21], 0
	v_mov_b64_e32 v[22:23], 0
	v_mov_b64_e32 v[28:29], 0
	v_mov_b64_e32 v[30:31], 0
	v_mov_b64_e32 v[36:37], 0
	v_mov_b64_e32 v[38:39], 0
	v_mov_b64_e32 v[44:45], 0
	v_mov_b64_e32 v[46:47], 0
	v_mov_b64_e32 v[52:53], 0
	v_mov_b64_e32 v[54:55], 0
	v_mov_b64_e32 v[56:57], 0
	v_mov_b64_e32 v[58:59], 0
	v_mov_b64_e32 v[60:61], 0
	v_mov_b64_e32 v[62:63], 0
	v_mov_b64_e32 v[64:65], 0
	v_mov_b64_e32 v[66:67], 0
	v_mov_b64_e32 v[68:69], 0
	v_mov_b64_e32 v[70:71], 0
	v_mov_b64_e32 v[72:73], 0
	v_mov_b64_e32 v[74:75], 0
	v_mov_b64_e32 v[80:81], 0
	v_mov_b64_e32 v[82:83], 0
	v_mov_b64_e32 v[88:89], 0
	v_mov_b64_e32 v[90:91], 0
	v_mov_b64_e32 v[96:97], 0
	v_mov_b64_e32 v[98:99], 0
	v_mov_b64_e32 v[104:105], 0
	v_mov_b64_e32 v[106:107], 0
	v_mov_b64_e32 v[112:113], 0
	v_mov_b64_e32 v[114:115], 0
	v_mov_b64_e32 v[76:77], 0
	v_mov_b64_e32 v[78:79], 0
	v_mov_b64_e32 v[84:85], 0
	v_mov_b64_e32 v[86:87], 0
	v_mov_b64_e32 v[92:93], 0
	v_mov_b64_e32 v[94:95], 0
	v_mov_b64_e32 v[100:101], 0
	v_mov_b64_e32 v[102:103], 0
	v_mov_b64_e32 v[108:109], 0
	v_mov_b64_e32 v[110:111], 0
	v_mov_b64_e32 v[116:117], 0
	v_mov_b64_e32 v[118:119], 0
	v_mov_b64_e32 v[120:121], 0
	v_mov_b64_e32 v[122:123], 0
	v_mov_b64_e32 v[124:125], 0
	v_mov_b64_e32 v[126:127], 0

; template <class Epi, class Sched, bool ALIGN_EPI = false, bool SP2 = false>
; __device__ __forceinline__ void gemm_phase(PG8_LAS unsigned char* lds, const Gemm g, const Sched& S, const Epi& E, int wave_s_) {
;     ...
; #pragma unroll
;         for (int a = 0; a < 2; ++a)
; #pragma unroll
;             for (int b = 0; b < 2; ++b)
; #pragma unroll
;                 for (int m = 0; m < 4; ++m)
; #pragma unroll
;                     for (int n = 0; n < 2; ++n) acc[a][b][m][n] = (f32x4){0.f, 0.f, 0.f, 0.f};
.LBB0_1357:
	v_mov_b32_e32 v0, 0
	s_mov_b32 s13, 0
	s_mov_b64 s[20:21], -1
	s_mov_b64 s[22:23], 0
	v_mov_b32_e32 v1, v0
	v_mov_b64_e32 v[2:3], 0
	v_mov_b64_e32 v[4:5], 0
	v_mov_b64_e32 v[6:7], 0
	v_mov_b64_e32 v[8:9], 0
	v_mov_b64_e32 v[10:11], 0
	v_mov_b64_e32 v[12:13], 0
	v_mov_b64_e32 v[14:15], 0
	v_mov_b64_e32 v[16:17], 0
	v_mov_b64_e32 v[18:19], 0
	v_mov_b64_e32 v[20:21], 0
	v_mov_b64_e32 v[22:23], 0
	v_mov_b64_e32 v[24:25], 0
	v_mov_b64_e32 v[26:27], 0
	v_mov_b64_e32 v[28:29], 0
	v_mov_b64_e32 v[30:31], 0
	v_mov_b64_e32 v[48:49], 0
	v_mov_b64_e32 v[50:51], 0
	v_mov_b64_e32 v[56:57], 0
	v_mov_b64_e32 v[58:59], 0
	v_mov_b64_e32 v[64:65], 0
	v_mov_b64_e32 v[66:67], 0
	v_mov_b64_e32 v[72:73], 0
	v_mov_b64_e32 v[74:75], 0
	v_mov_b64_e32 v[80:81], 0
	v_mov_b64_e32 v[82:83], 0
	v_mov_b64_e32 v[84:85], 0
	v_mov_b64_e32 v[86:87], 0
	v_mov_b64_e32 v[88:89], 0
	v_mov_b64_e32 v[90:91], 0
	v_mov_b64_e32 v[92:93], 0
	v_mov_b64_e32 v[94:95], 0
	v_mov_b64_e32 v[32:33], 0
	v_mov_b64_e32 v[34:35], 0
	v_mov_b64_e32 v[36:37], 0
	v_mov_b64_e32 v[38:39], 0
	v_mov_b64_e32 v[40:41], 0
	v_mov_b64_e32 v[42:43], 0
	v_mov_b64_e32 v[44:45], 0
	v_mov_b64_e32 v[46:47], 0
	v_mov_b64_e32 v[52:53], 0
	v_mov_b64_e32 v[54:55], 0
	v_mov_b64_e32 v[60:61], 0
	v_mov_b64_e32 v[62:63], 0
	v_mov_b64_e32 v[68:69], 0
	v_mov_b64_e32 v[70:71], 0
	v_mov_b64_e32 v[76:77], 0
	v_mov_b64_e32 v[78:79], 0
	v_mov_b64_e32 v[96:97], 0
	v_mov_b64_e32 v[98:99], 0
	v_mov_b64_e32 v[100:101], 0
	v_mov_b64_e32 v[102:103], 0
	v_mov_b64_e32 v[104:105], 0
	v_mov_b64_e32 v[106:107], 0
	v_mov_b64_e32 v[108:109], 0
	v_mov_b64_e32 v[110:111], 0
	v_mov_b64_e32 v[112:113], 0
	v_mov_b64_e32 v[114:115], 0
	v_mov_b64_e32 v[116:117], 0
	v_mov_b64_e32 v[118:119], 0
	v_mov_b64_e32 v[120:121], 0
	v_mov_b64_e32 v[122:123], 0
	v_mov_b64_e32 v[124:125], 0
	v_mov_b64_e32 v[126:127], 0

; template <int DQ, bool BIAS, bool TAIL>
; __device__ __forceinline__ void attn_item(const AttnItem& A, LAS unsigned char* lds, int wave_s_) {
;     ...
;     f32x16 o[2][2];
;     float zinit = 0.f; asm volatile("" : "+v"(zinit));
;     const f32x16 zero16v = {0.f, 0.f, 0.f, 0.f, 0.f, 0.f, 0.f, 0.f, 0.f, 0.f, 0.f, 0.f, 0.f, 0.f, 0.f, 0.f};
;     float mref[2] = {A.m0, A.m0};
; #pragma unroll
;     for (int qb = 0; qb < 2; ++qb)
; #pragma unroll
;         for (int i = 0; i < 16; ++i) { o[0][qb][i] = zinit; o[1][qb][i] = zinit; }
;     float lrun[2] = {hi == 0 ? A.l0 : 0.f, hi == 0 ? A.l0 : 0.f};
;     bool first = A.l0 == 0.f;
;     const int lkey = tid >> 3, lpc = tid & 7, l2key = tid >> 2, l2pc = tid & 3;
.LBB0_1439:
	v_lshlrev_b32_e32 v222, 2, v12
	v_lshrrev_b32_e32 v1, 2, v11
	v_and_b32_e32 v2, 16, v11
	v_lshlrev_b32_e32 v3, 2, v11
	v_and_b32_e32 v17, 63, v11
	v_and_or_b32 v1, v1, 3, v222
	v_and_or_b32 v2, v3, 12, v2
	s_movk_i32 s4, 0x48
	v_mad_u32_u24 v18, v1, s4, v2
	v_mul_u32_u24_e32 v19, 0xd0, v220
	v_mov_b64_e32 v[14:15], 0
	v_cmp_gt_u32_e64 s[4:5], 32, v17
	v_mov_b32_e32 v17, v197
	v_mov_b32_e32 v1, v0
	v_mov_b64_e32 v[2:3], 0
	v_mov_b64_e32 v[4:5], 0
	v_mov_b64_e32 v[6:7], 0
	v_mov_b64_e32 v[8:9], 0
	v_mov_b64_e32 v[10:11], 0
	v_mov_b64_e32 v[12:13], 0
	v_add3_u32 v228, 0, v196, v19
	v_lshl_add_u32 v227, v18, 1, 0
	v_lshl_add_u64 v[214:215], s[46:47], 0, v[16:17]
	v_lshl_add_u64 v[216:217], s[48:49], 0, v[16:17]
	v_mov_b32_e32 v211, v197
	v_mov_b32_e32 v196, v197
	v_mov_b64_e32 v[46:47], v[14:15]
	v_mov_b64_e32 v[30:31], v[14:15]
	v_mov_b64_e32 v[62:63], v[14:15]
	s_min_i32 s70, s69, s66
	v_lshl_add_u64 v[218:219], s[40:41], 0, v[210:211]
	s_lshl_b32 s71, s66, 6
	s_add_i32 s74, s72, 64
	s_mov_b32 s75, 0
	s_mov_b64 s[54:55], -1
	v_mov_b32_e32 v223, 0
	v_mov_b64_e32 v[44:45], v[12:13]
	v_mov_b64_e32 v[42:43], v[10:11]
	v_mov_b64_e32 v[40:41], v[8:9]
	v_mov_b64_e32 v[38:39], v[6:7]
	v_mov_b64_e32 v[36:37], v[4:5]
	v_mov_b64_e32 v[34:35], v[2:3]
	v_mov_b64_e32 v[32:33], v[0:1]
	v_mov_b64_e32 v[28:29], v[12:13]
	v_mov_b64_e32 v[26:27], v[10:11]
	v_mov_b64_e32 v[24:25], v[8:9]
	v_mov_b64_e32 v[22:23], v[6:7]
	v_mov_b64_e32 v[20:21], v[4:5]
	v_mov_b64_e32 v[18:19], v[2:3]
	v_mov_b64_e32 v[16:17], v[0:1]
	v_mov_b64_e32 v[60:61], v[12:13]
	v_mov_b64_e32 v[58:59], v[10:11]
	v_mov_b64_e32 v[56:57], v[8:9]
	v_mov_b64_e32 v[54:55], v[6:7]
	v_mov_b64_e32 v[52:53], v[4:5]
	v_mov_b64_e32 v[50:51], v[2:3]
	v_mov_b64_e32 v[48:49], v[0:1]
	v_mov_b32_e32 v211, 0
	s_mov_b32 s78, 0
	s_mov_b32 s79, 0
	v_mov_b64_e32 v[212:213], v[196:197]
	s_branch .LBB0_1441

; template <int DQ, bool BIAS, bool TAIL>
; __device__ __forceinline__ void attn_item(const AttnItem& A, LAS unsigned char* lds, int wave_s_) {
;     ...
;     f32x16 o[2][2];
;     float zinit = 0.f; asm volatile("" : "+v"(zinit));
;     const f32x16 zero16v = {0.f, 0.f, 0.f, 0.f, 0.f, 0.f, 0.f, 0.f, 0.f, 0.f, 0.f, 0.f, 0.f, 0.f, 0.f, 0.f};
;     float mref[2] = {A.m0, A.m0};
; #pragma unroll
;     for (int qb = 0; qb < 2; ++qb)
; #pragma unroll
;         for (int i = 0; i < 16; ++i) { o[0][qb][i] = zinit; o[1][qb][i] = zinit; }
;     float lrun[2] = {hi == 0 ? A.l0 : 0.f, hi == 0 ? A.l0 : 0.f};
;     bool first = A.l0 == 0.f;
;     const int lkey = tid >> 3, lpc = tid & 7, l2key = tid >> 2, l2pc = tid & 3;
.LBB0_1472:
	v_lshlrev_b32_e32 v222, 2, v12
	v_lshrrev_b32_e32 v1, 2, v11
	v_and_b32_e32 v2, 16, v11
	v_lshlrev_b32_e32 v3, 2, v11
	v_and_b32_e32 v17, 63, v11
	v_and_or_b32 v1, v1, 3, v222
	v_and_or_b32 v2, v3, 12, v2
	s_movk_i32 s1, 0x48
	v_mad_u32_u24 v18, v1, s1, v2
	v_mul_u32_u24_e32 v19, 0xd0, v220
	v_mov_b64_e32 v[14:15], 0
	v_cmp_gt_u32_e64 s[4:5], 32, v17
	v_mov_b32_e32 v17, v197
	v_mov_b32_e32 v1, v0
	v_mov_b64_e32 v[2:3], 0
	v_mov_b64_e32 v[4:5], 0
	v_mov_b64_e32 v[6:7], 0
	v_mov_b64_e32 v[8:9], 0
	v_mov_b64_e32 v[10:11], 0
	v_mov_b64_e32 v[12:13], 0
	v_add3_u32 v228, 0, v196, v19
	v_lshl_add_u32 v227, v18, 1, 0
	v_lshl_add_u64 v[214:215], s[46:47], 0, v[16:17]
	v_lshl_add_u64 v[216:217], s[48:49], 0, v[16:17]
	v_mov_b32_e32 v211, v197
	v_mov_b32_e32 v196, v197
	v_mov_b64_e32 v[46:47], v[14:15]
	v_mov_b64_e32 v[30:31], v[14:15]
	v_mov_b64_e32 v[62:63], v[14:15]
	s_min_i32 s1, s20, s66
	v_lshl_add_u64 v[218:219], s[40:41], 0, v[210:211]
	s_add_i32 s18, s72, 64
	s_mov_b32 s21, 0
	s_mov_b64 s[16:17], -1
	s_mov_b64 s[100:101], -1
	v_mov_b32_e32 v223, 0
	v_mov_b64_e32 v[44:45], v[12:13]
	v_mov_b64_e32 v[42:43], v[10:11]
	v_mov_b64_e32 v[40:41], v[8:9]
	v_mov_b64_e32 v[38:39], v[6:7]
	v_mov_b64_e32 v[36:37], v[4:5]
	v_mov_b64_e32 v[34:35], v[2:3]
	v_mov_b64_e32 v[32:33], v[0:1]
	v_mov_b64_e32 v[28:29], v[12:13]
	v_mov_b64_e32 v[26:27], v[10:11]
	v_mov_b64_e32 v[24:25], v[8:9]
	v_mov_b64_e32 v[22:23], v[6:7]
	v_mov_b64_e32 v[20:21], v[4:5]
	v_mov_b64_e32 v[18:19], v[2:3]
	v_mov_b64_e32 v[16:17], v[0:1]
	v_mov_b64_e32 v[60:61], v[12:13]
	v_mov_b64_e32 v[58:59], v[10:11]
	v_mov_b64_e32 v[56:57], v[8:9]
	v_mov_b64_e32 v[54:55], v[6:7]
	v_mov_b64_e32 v[52:53], v[4:5]
	v_mov_b64_e32 v[50:51], v[2:3]
	v_mov_b64_e32 v[48:49], v[0:1]
	v_mov_b32_e32 v211, 0
	s_mov_b32 s22, 0
	v_mov_b64_e32 v[212:213], v[196:197]
	s_branch .LBB0_1474

;     __device__ __forceinline__ int nt_of(const Unit& u) const { return (u.pm >> 12) ? ktper : kt; }
; template <class Epi, class Sched, bool ALIGN_EPI = false, bool SP2 = false>
; __device__ __forceinline__ void gemm_phase(PG8_LAS unsigned char* lds, const Gemm g, const Sched& S, const Epi& E, int wave_s_) {
;     ...
;         const int nt = S.nt_of(cur);
;         for (int t = 0; t < nt; t += 2) {
;     ...
; #pragma unroll
;         for (int a = 0; a < 2; ++a)
; #pragma unroll
;             for (int b = 0; b < 2; ++b)
; #pragma unroll
;                 for (int m = 0; m < 4; ++m)
; #pragma unroll
;                     for (int n = 0; n < 2; ++n) acc[a][b][m][n] = (f32x4){0.f, 0.f, 0.f, 0.f};
.LBB0_1580:
	s_cmpk_gt_u32 s54, 0xfff
	s_cselect_b64 s[26:27], -1, 0
	s_cmpk_lt_u32 s54, 0x1000
	s_cselect_b64 s[6:7], -1, 0
	s_and_b64 s[30:31], s[6:7], exec
	s_cselect_b32 s9, 16, 4
	s_add_i32 s21, s9, -2
	s_add_u32 s55, s28, 0x100
	v_mov_b32_e32 v0, 0
	s_addc_u32 s56, s29, 0
	s_mov_b32 s30, 0
	v_mov_b32_e32 v1, v0
	v_mov_b64_e32 v[2:3], 0
	v_mov_b64_e32 v[4:5], 0
	v_mov_b64_e32 v[6:7], 0
	v_mov_b64_e32 v[12:13], 0
	v_mov_b64_e32 v[14:15], 0
	v_mov_b64_e32 v[20:21], 0
	v_mov_b64_e32 v[22:23], 0
	v_mov_b64_e32 v[32:33], 0
	v_mov_b64_e32 v[34:35], 0
	v_mov_b64_e32 v[36:37], 0
	v_mov_b64_e32 v[38:39], 0
	v_mov_b64_e32 v[44:45], 0
	v_mov_b64_e32 v[46:47], 0
	v_mov_b64_e32 v[52:53], 0
	v_mov_b64_e32 v[54:55], 0
	v_mov_b64_e32 v[8:9], 0
	v_mov_b64_e32 v[10:11], 0
	v_mov_b64_e32 v[16:17], 0
	v_mov_b64_e32 v[18:19], 0
	v_mov_b64_e32 v[24:25], 0
	v_mov_b64_e32 v[26:27], 0
	v_mov_b64_e32 v[28:29], 0
	v_mov_b64_e32 v[30:31], 0
	v_mov_b64_e32 v[40:41], 0
	v_mov_b64_e32 v[42:43], 0
	v_mov_b64_e32 v[48:49], 0
	v_mov_b64_e32 v[50:51], 0
	v_mov_b64_e32 v[56:57], 0
	v_mov_b64_e32 v[58:59], 0
	v_mov_b64_e32 v[60:61], 0
	v_mov_b64_e32 v[62:63], 0
	v_mov_b64_e32 v[64:65], 0
	v_mov_b64_e32 v[66:67], 0
	v_mov_b64_e32 v[68:69], 0
	v_mov_b64_e32 v[70:71], 0
	v_mov_b64_e32 v[76:77], 0
	v_mov_b64_e32 v[78:79], 0
	v_mov_b64_e32 v[84:85], 0
	v_mov_b64_e32 v[86:87], 0
	s_waitcnt vmcnt(0)
	v_mov_b64_e32 v[128:129], 0
	v_mov_b64_e32 v[130:131], 0
	v_mov_b64_e32 v[132:133], 0
	v_mov_b64_e32 v[134:135], 0
	v_mov_b64_e32 v[140:141], 0
	v_mov_b64_e32 v[142:143], 0
	v_mov_b64_e32 v[148:149], 0
	v_mov_b64_e32 v[150:151], 0
	v_mov_b64_e32 v[72:73], 0
	v_mov_b64_e32 v[74:75], 0
	v_mov_b64_e32 v[80:81], 0
	v_mov_b64_e32 v[82:83], 0
	v_mov_b64_e32 v[104:105], 0
	v_mov_b64_e32 v[106:107], 0
	v_mov_b64_e32 v[124:125], 0
	v_mov_b64_e32 v[126:127], 0
	v_mov_b64_e32 v[136:137], 0
	v_mov_b64_e32 v[138:139], 0
	v_mov_b64_e32 v[144:145], 0
	v_mov_b64_e32 v[146:147], 0
	v_mov_b64_e32 v[152:153], 0
	v_mov_b64_e32 v[154:155], 0
	v_mov_b64_e32 v[156:157], 0
	v_mov_b64_e32 v[158:159], 0

; template <class Epi, class Sched, bool ALIGN_EPI = false, bool SP2 = false>
; __device__ __forceinline__ void gemm_phase(PG8_LAS unsigned char* lds, const Gemm g, const Sched& S, const Epi& E, int wave_s_) {
;     ...
; #pragma unroll
;         for (int a = 0; a < 2; ++a)
; #pragma unroll
;             for (int b = 0; b < 2; ++b)
; #pragma unroll
;                 for (int m = 0; m < 4; ++m)
; #pragma unroll
;                     for (int n = 0; n < 2; ++n) acc[a][b][m][n] = (f32x4){0.f, 0.f, 0.f, 0.f};
.LBB0_1819:
	s_add_u32 s15, s18, 0x100
	s_addc_u32 s45, s19, 0
	s_add_u32 s18, s20, 0x40080
	v_mov_b32_e32 v0, 0
	s_addc_u32 s19, s21, 0
	s_mov_b32 s46, -2
	v_mov_b32_e32 v1, v0
	v_mov_b64_e32 v[2:3], 0
	v_mov_b64_e32 v[8:9], 0
	v_mov_b64_e32 v[10:11], 0
	v_mov_b64_e32 v[16:17], 0
	v_mov_b64_e32 v[18:19], 0
	v_mov_b64_e32 v[24:25], 0
	v_mov_b64_e32 v[26:27], 0
	v_mov_b64_e32 v[32:33], 0
	v_mov_b64_e32 v[34:35], 0
	v_mov_b64_e32 v[40:41], 0
	v_mov_b64_e32 v[42:43], 0
	v_mov_b64_e32 v[48:49], 0
	v_mov_b64_e32 v[50:51], 0
	v_mov_b64_e32 v[56:57], 0
	v_mov_b64_e32 v[58:59], 0
	v_mov_b64_e32 v[4:5], 0
	v_mov_b64_e32 v[6:7], 0
	v_mov_b64_e32 v[12:13], 0
	v_mov_b64_e32 v[14:15], 0
	v_mov_b64_e32 v[20:21], 0
	v_mov_b64_e32 v[22:23], 0
	v_mov_b64_e32 v[28:29], 0
	v_mov_b64_e32 v[30:31], 0
	v_mov_b64_e32 v[36:37], 0
	v_mov_b64_e32 v[38:39], 0
	v_mov_b64_e32 v[44:45], 0
	v_mov_b64_e32 v[46:47], 0
	v_mov_b64_e32 v[52:53], 0
	v_mov_b64_e32 v[54:55], 0
	v_mov_b64_e32 v[60:61], 0
	v_mov_b64_e32 v[62:63], 0
	v_mov_b64_e32 v[64:65], 0
	v_mov_b64_e32 v[66:67], 0
	v_mov_b64_e32 v[72:73], 0
	v_mov_b64_e32 v[74:75], 0
	v_mov_b64_e32 v[80:81], 0
	v_mov_b64_e32 v[82:83], 0
	v_mov_b64_e32 v[88:89], 0
	v_mov_b64_e32 v[90:91], 0
	v_mov_b64_e32 v[96:97], 0
	v_mov_b64_e32 v[98:99], 0
	v_mov_b64_e32 v[104:105], 0
	v_mov_b64_e32 v[106:107], 0
	v_mov_b64_e32 v[112:113], 0
	v_mov_b64_e32 v[114:115], 0
	v_mov_b64_e32 v[120:121], 0
	v_mov_b64_e32 v[122:123], 0
	v_mov_b64_e32 v[68:69], 0
	v_mov_b64_e32 v[70:71], 0
	v_mov_b64_e32 v[76:77], 0
	v_mov_b64_e32 v[78:79], 0
	v_mov_b64_e32 v[84:85], 0
	v_mov_b64_e32 v[86:87], 0
	v_mov_b64_e32 v[92:93], 0
	v_mov_b64_e32 v[94:95], 0
	v_mov_b64_e32 v[100:101], 0
	v_mov_b64_e32 v[102:103], 0
	v_mov_b64_e32 v[108:109], 0
	v_mov_b64_e32 v[110:111], 0
	v_mov_b64_e32 v[116:117], 0
	v_mov_b64_e32 v[118:119], 0
	v_mov_b64_e32 v[124:125], 0
	v_mov_b64_e32 v[126:127], 0

;     __device__ __forceinline__ int nt_of(const Unit& u) const { return (u.pm >> 12) ? ktper : kt; }
; template <class Epi, class Sched, bool ALIGN_EPI = false, bool SP2 = false>
; __device__ __forceinline__ void gemm_phase(PG8_LAS unsigned char* lds, const Gemm g, const Sched& S, const Epi& E, int wave_s_) {
;     ...
;         const int nt = S.nt_of(cur);
;         for (int t = 0; t < nt; t += 2) {
;     ...
; #pragma unroll
;         for (int a = 0; a < 2; ++a)
; #pragma unroll
;             for (int b = 0; b < 2; ++b)
; #pragma unroll
;                 for (int m = 0; m < 4; ++m)
; #pragma unroll
;                     for (int n = 0; n < 2; ++n) acc[a][b][m][n] = (f32x4){0.f, 0.f, 0.f, 0.f};
.LBB0_1907:
	s_cmpk_gt_u32 s51, 0xfff
	s_cselect_b64 s[24:25], -1, 0
	s_cmpk_lt_u32 s51, 0x1000
	s_cselect_b64 s[6:7], -1, 0
	s_and_b64 s[26:27], s[6:7], exec
	s_cselect_b32 s53, 44, 4
	s_add_i32 s54, s53, -2
	s_add_u32 s55, s10, 0x100
	v_mov_b32_e32 v0, 0
	s_addc_u32 s56, s11, 0
	s_mov_b32 s26, 0
	v_mov_b32_e32 v1, v0
	v_mov_b64_e32 v[2:3], 0
	v_mov_b64_e32 v[4:5], 0
	v_mov_b64_e32 v[6:7], 0
	v_mov_b64_e32 v[12:13], 0
	v_mov_b64_e32 v[14:15], 0
	v_mov_b64_e32 v[20:21], 0
	v_mov_b64_e32 v[22:23], 0
	v_mov_b64_e32 v[32:33], 0
	v_mov_b64_e32 v[34:35], 0
	v_mov_b64_e32 v[36:37], 0
	v_mov_b64_e32 v[38:39], 0
	v_mov_b64_e32 v[44:45], 0
	v_mov_b64_e32 v[46:47], 0
	v_mov_b64_e32 v[52:53], 0
	v_mov_b64_e32 v[54:55], 0
	v_mov_b64_e32 v[8:9], 0
	v_mov_b64_e32 v[10:11], 0
	v_mov_b64_e32 v[16:17], 0
	v_mov_b64_e32 v[18:19], 0
	v_mov_b64_e32 v[24:25], 0
	v_mov_b64_e32 v[26:27], 0
	v_mov_b64_e32 v[28:29], 0
	v_mov_b64_e32 v[30:31], 0
	v_mov_b64_e32 v[40:41], 0
	v_mov_b64_e32 v[42:43], 0
	v_mov_b64_e32 v[48:49], 0
	v_mov_b64_e32 v[50:51], 0
	v_mov_b64_e32 v[56:57], 0
	v_mov_b64_e32 v[58:59], 0
	v_mov_b64_e32 v[60:61], 0
	v_mov_b64_e32 v[62:63], 0
	v_mov_b64_e32 v[64:65], 0
	v_mov_b64_e32 v[66:67], 0
	v_mov_b64_e32 v[68:69], 0
	v_mov_b64_e32 v[70:71], 0
	v_mov_b64_e32 v[80:81], 0
	v_mov_b64_e32 v[82:83], 0
	v_mov_b64_e32 v[96:97], 0
	v_mov_b64_e32 v[98:99], 0
	v_mov_b64_e32 v[128:129], 0
	v_mov_b64_e32 v[130:131], 0
	v_mov_b64_e32 v[132:133], 0
	v_mov_b64_e32 v[134:135], 0
	v_mov_b64_e32 v[140:141], 0
	v_mov_b64_e32 v[142:143], 0
	v_mov_b64_e32 v[148:149], 0
	v_mov_b64_e32 v[150:151], 0
	v_mov_b64_e32 v[72:73], 0
	v_mov_b64_e32 v[74:75], 0
	v_mov_b64_e32 v[88:89], 0
	v_mov_b64_e32 v[90:91], 0
	v_mov_b64_e32 v[116:117], 0
	v_mov_b64_e32 v[118:119], 0
	v_mov_b64_e32 v[124:125], 0
	v_mov_b64_e32 v[126:127], 0
	v_mov_b64_e32 v[136:137], 0
	v_mov_b64_e32 v[138:139], 0
	v_mov_b64_e32 v[144:145], 0
	v_mov_b64_e32 v[146:147], 0
	v_mov_b64_e32 v[152:153], 0
	v_mov_b64_e32 v[154:155], 0
	v_mov_b64_e32 v[156:157], 0
	v_mov_b64_e32 v[158:159], 0
